# D latent tiles: waves 4-7 (second softmax group) start each tile 256 cycles after waves 0-3 so MFMA-only and VALU-only sub-phases of the two waves on a SIMD overlap
# speedup vs baseline: 1.0025x; 1.0023x over previous
; #define LAS __attribute__((address_space(3)))
; DI unsigned pk2(float lo, float hi) { f32x2 v = {lo, hi}; bf16x2_t b = __builtin_convertvector(v, bf16x2_t); return __builtin_bit_cast(unsigned, b); }
; DI float fast_exp2(float x) { return __builtin_amdgcn_exp2f(x); }
; DI void attn_unit_d32(const Ctx& C, const bf16_t* __restrict__ Z, bf16_t* __restrict__ Y, int b, int qsel, int hsel, bool ctxq, float lam, float post_scale, const float* subln, const float mref) {
;     ...
;         const LAS bf16_t* Ks = lds16 + ((t & 1) * AT_BUF) / 2 + 64 * sm; const LAS bf16_t* Vt = lds16 + ((t & 1) * AT_BUF + AT_VT) / 2;
;         f32x16 st[2];
; #pragma unroll
;         for (int kb = 0; kb < 2; ++kb) {
; #pragma unroll
;             for (int r = 0; r < 16; ++r) st[kb][r] = negm;
; #pragma unroll
;             for (int ks = 0; ks < 4; ++ks) { const bf16x8 a = *(const LAS bf16x8*)(Ks + (32 * kb + l31) * KST + 16 * ks + 8 * hh);
;                 st[kb] = __builtin_amdgcn_mfma_f32_32x32x16_bf16(a, qf[ks], st[kb], 0, 0, 0); } }
;         bf16x8 pf[2][2]; float ps = 0.f;
; #pragma unroll
;         for (int kb = 0; kb < 2; ++kb) {
; #pragma unroll
;             for (int r = 0; r < 16; ++r) { const float p = fast_exp2(st[kb][r]); st[kb][r] = p; ps += p; }
; #pragma unroll
;             for (int s = 0; s < 2; ++s) { u32x4 pw; pw.x = pk2(st[kb][8 * s], st[kb][8 * s + 1]); pw.y = pk2(st[kb][8 * s + 2], st[kb][8 * s + 3]); pw.z = pk2(st[kb][8 * s + 4], st[kb][8 * s + 5]); pw.w = pk2(st[kb][8 * s + 6], st[kb][8 * s + 7]);
;                 pf[kb][s] = __builtin_bit_cast(bf16x8, pw); } }
;         lsum += ps;
; #pragma unroll
;         for (int d = 0; d < 4; ++d)
; #pragma unroll
;             for (int kb = 0; kb < 2; ++kb)
; #pragma unroll
;                 for (int s = 0; s < 2; ++s) { const LAS bf16_t* vp = Vt + (32 * d + l31) * VST + 32 * kb + 16 * s + 4 * hh;
;                     const u32x2 lo = *(const LAS u32x2*)vp, hi = *(const LAS u32x2*)(vp + 8);
;                     u32x4 av; av.x = lo.x; av.y = lo.y; av.z = hi.x; av.w = hi.y;
;                     o[d] = __builtin_amdgcn_mfma_f32_32x32x16_bf16(__builtin_bit_cast(bf16x8, av), pf[kb][s], o[d], 0, 0, 0); }
.LBB0_399:
.LBB0_407:
	v_readfirstlane_b32 s2, v208
	s_nop 0
	s_bitcmp1_b32 s2, 8
	s_cbranch_scc0 .Ldskew_a
	s_sleep 4
.Ldskew_a:
	s_add_i32 s0, s23, 1
	s_bitcmp1_b32 s23, 0
	s_cselect_b32 s1, 0x9000, 0
	s_lshl_b32 s24, s18, 1
	s_add_i32 s24, s1, s24
	v_add3_u32 v194, s24, v183, v184
	ds_read_b128 v[84:87], v194
	ds_read_b128 v[88:91], v194 offset:32
	ds_read_b128 v[92:95], v194 offset:64
	ds_read_b128 v[96:99], v194 offset:96
	ds_read_b128 v[214:217], v194 offset:8704
	ds_read_b128 v[218:221], v194 offset:8736
	ds_read_b128 v[222:225], v194 offset:8768
	ds_read_b128 v[240:243], v194 offset:8800
	v_add3_u32 v195, s1, v183, v185
	ds_read_b128 v[244:247], v195 offset:17408
	ds_read_b128 v[210:213], v195 offset:17440
	s_waitcnt lgkmcnt(9)
	v_mfma_f32_32x32x16_bf16 v[100:115], v[84:87], v[116:119], v[4:19]
	s_waitcnt lgkmcnt(8)
	v_mfma_f32_32x32x16_bf16 v[100:115], v[88:91], v[120:123], v[100:115]
	s_waitcnt lgkmcnt(7)
	v_mfma_f32_32x32x16_bf16 v[100:115], v[92:95], v[124:127], v[100:115]
	s_waitcnt lgkmcnt(6)
	v_mfma_f32_32x32x16_bf16 v[100:115], v[96:99], v[128:131], v[100:115]
	s_waitcnt lgkmcnt(5)
	v_mfma_f32_32x32x16_bf16 v[84:99], v[214:217], v[116:119], v[4:19]
	ds_read_b128 v[214:217], v195 offset:22016
	s_waitcnt lgkmcnt(5)
	v_mfma_f32_32x32x16_bf16 v[84:99], v[218:221], v[120:123], v[84:99]
	ds_read_b128 v[218:221], v195 offset:22048
	s_waitcnt lgkmcnt(5)
	v_mfma_f32_32x32x16_bf16 v[84:99], v[222:225], v[124:127], v[84:99]
	ds_read_b128 v[222:225], v195 offset:26624
	s_waitcnt lgkmcnt(5)
	v_mfma_f32_32x32x16_bf16 v[84:99], v[240:243], v[128:131], v[84:99]
	ds_read_b128 v[240:243], v195 offset:26656
	v_exp_f32_e32 v100, v100
	v_exp_f32_e32 v101, v101
	v_exp_f32_e32 v102, v102
	v_add_f32_e32 v209, v101, v100
	v_exp_f32_e32 v103, v103
	v_add_f32_e32 v209, v102, v209
	v_exp_f32_e32 v104, v104
	v_add_f32_e32 v209, v103, v209
	v_exp_f32_e32 v105, v105
	v_add_f32_e32 v209, v104, v209
	v_exp_f32_e32 v106, v106
	v_add_f32_e32 v209, v105, v209
	v_exp_f32_e32 v107, v107
	v_add_f32_e32 v209, v106, v209
	v_exp_f32_e32 v108, v108
	v_add_f32_e32 v209, v107, v209
	v_exp_f32_e32 v109, v109
	v_add_f32_e32 v209, v108, v209
	v_exp_f32_e32 v110, v110
	v_add_f32_e32 v209, v109, v209
	v_exp_f32_e32 v111, v111
	v_add_f32_e32 v209, v110, v209
	v_exp_f32_e32 v112, v112
	v_add_f32_e32 v209, v111, v209
	v_exp_f32_e32 v113, v113
	v_add_f32_e32 v209, v112, v209
	v_exp_f32_e32 v114, v114
	v_add_f32_e32 v209, v113, v209
	v_exp_f32_e32 v115, v115
	v_add_f32_e32 v209, v114, v209
	v_cvt_pk_bf16_f32 v100, v100, v101
	v_add_f32_e32 v209, v115, v209
	v_cvt_pk_bf16_f32 v101, v102, v103
	v_cvt_pk_bf16_f32 v102, v104, v105
	v_cvt_pk_bf16_f32 v103, v106, v107
	v_cvt_pk_bf16_f32 v104, v108, v109
	v_cvt_pk_bf16_f32 v105, v110, v111
	v_cvt_pk_bf16_f32 v106, v112, v113
	v_cvt_pk_bf16_f32 v107, v114, v115
	ds_read_b128 v[108:111], v195 offset:31232
	ds_read_b128 v[112:115], v195 offset:31264
	s_waitcnt lgkmcnt(7)
	v_mfma_f32_32x32x16_bf16 v[68:83], v[244:247], v[100:103], v[68:83]
	ds_read_b128 v[244:247], v195 offset:17472
	v_exp_f32_e32 v84, v84
	v_exp_f32_e32 v85, v85
	v_add_f32_e32 v209, v84, v209
	v_exp_f32_e32 v86, v86
	v_add_f32_e32 v209, v85, v209
	s_waitcnt lgkmcnt(7)
	v_mfma_f32_32x32x16_bf16 v[68:83], v[210:213], v[104:107], v[68:83]
	ds_read_b128 v[210:213], v195 offset:17504
	v_exp_f32_e32 v87, v87
	v_add_f32_e32 v209, v86, v209
	v_exp_f32_e32 v88, v88
	v_add_f32_e32 v209, v87, v209
	v_exp_f32_e32 v89, v89
	s_waitcnt lgkmcnt(7)
	v_mfma_f32_32x32x16_bf16 v[52:67], v[214:217], v[100:103], v[52:67]
	ds_read_b128 v[214:217], v195 offset:22080
	v_add_f32_e32 v209, v88, v209
	v_exp_f32_e32 v90, v90
	v_add_f32_e32 v209, v89, v209
	v_exp_f32_e32 v91, v91
	v_add_f32_e32 v209, v90, v209
	s_waitcnt lgkmcnt(7)
	v_mfma_f32_32x32x16_bf16 v[52:67], v[218:221], v[104:107], v[52:67]
	ds_read_b128 v[218:221], v195 offset:22112
	v_exp_f32_e32 v92, v92
	v_add_f32_e32 v209, v91, v209
	v_exp_f32_e32 v93, v93
	v_add_f32_e32 v209, v92, v209
	v_exp_f32_e32 v94, v94
	s_waitcnt lgkmcnt(7)
	v_mfma_f32_32x32x16_bf16 v[36:51], v[222:225], v[100:103], v[36:51]
	ds_read_b128 v[222:225], v195 offset:26688
	v_add_f32_e32 v209, v93, v209
	v_exp_f32_e32 v95, v95
	v_add_f32_e32 v209, v94, v209
	v_exp_f32_e32 v96, v96
	v_add_f32_e32 v209, v95, v209
	s_waitcnt lgkmcnt(7)
	v_mfma_f32_32x32x16_bf16 v[36:51], v[240:243], v[104:107], v[36:51]
	ds_read_b128 v[240:243], v195 offset:26720
	v_exp_f32_e32 v97, v97
	v_add_f32_e32 v209, v96, v209
	v_exp_f32_e32 v98, v98
	v_add_f32_e32 v209, v97, v209
	v_exp_f32_e32 v99, v99
	s_waitcnt lgkmcnt(7)
	v_mfma_f32_32x32x16_bf16 v[20:35], v[108:111], v[100:103], v[20:35]
	ds_read_b128 v[108:111], v195 offset:31296
	v_add_f32_e32 v209, v98, v209
	v_cvt_pk_bf16_f32 v84, v84, v85
	v_add_f32_e32 v209, v99, v209
	v_cvt_pk_bf16_f32 v85, v86, v87
	v_cvt_pk_bf16_f32 v86, v88, v89
	s_waitcnt lgkmcnt(7)
	v_mfma_f32_32x32x16_bf16 v[20:35], v[112:115], v[104:107], v[20:35]
	ds_read_b128 v[112:115], v195 offset:31328
	v_cvt_pk_bf16_f32 v87, v90, v91
	v_cvt_pk_bf16_f32 v88, v92, v93
	v_cvt_pk_bf16_f32 v89, v94, v95
	v_cvt_pk_bf16_f32 v90, v96, v97
	v_cvt_pk_bf16_f32 v91, v98, v99
	s_cmp_gt_u32 s23, 34
	s_cbranch_scc1 .Ldt_plain
	s_bitcmp1_b32 s23, 0
	s_cbranch_scc0 .Ldt_even
